# P7 norm of slab-0 rows moved onto idle workgroups during slab-1 P5 tail; P8 A-tile index remapped
# baseline (speedup 1.0000x reference)
; __device__ __forceinline__ unsigned xb_ld(unsigned* p)              { return __hip_atomic_load(p, __ATOMIC_RELAXED, __HIP_MEMORY_SCOPE_AGENT); }
; __device__ __forceinline__ void xcd_barrier_complete(unsigned* bar, unsigned x, unsigned& nloc, unsigned& nx) {
;     const unsigned G = gridDim.x * gridDim.y * gridDim.z;
;     unsigned sum, cnt, mine, sp = 0u;
;     for (;;) {
;         sum = 0u; cnt = 0u; mine = 0u;
; #pragma unroll
;         for (unsigned j = 0; j < 16; ++j) { const unsigned c = xb_ld(&bar[XB_XCNT(j)]); sum += c; cnt += (c > 0u) ? 1u : 0u; mine = (j == x) ? c : mine; }
; __global__ void __launch_bounds__(512, 2) mega_fwd(Args a) {
;     ...
;     bf16_t* Hb = (bf16_t*)(a.ws + WS_H); bf16_t* proj = (bf16_t*)(a.ws + WS_PROJ); float* ssq = (float*)(a.ws + WS_SSQ);
;     const float* modall = (const float*)(a.ws + WS_MOD);
.LBB0_132:
	s_or_b64 exec, exec, s[4:5]
	s_add_u32 s12, s26, 0x5880000
	s_addc_u32 s13, s27, 0
	s_add_u32 s18, s26, 0x9c80000
	s_addc_u32 s19, s27, 0
	s_add_u32 s4, s26, 0x5640000
	s_addc_u32 s5, s27, 0
	v_writelane_b32 v252, s4, 39
	v_mov_b32_e32 v1, 0
	v_mbcnt_lo_u32_b32 v0, -1, 0
	v_writelane_b32 v252, s5, 40
	s_add_u32 s4, s26, 0x5400000
	v_writelane_b32 v252, s4, 41
	s_addc_u32 s4, s27, 0
	v_writelane_b32 v252, s4, 42
	s_add_u32 s34, s24, 0x8000000
	v_readlane_b32 s16, v252, 0
	s_addc_u32 s35, s25, 0
	s_lshl_b32 s6, s16, 4
	s_add_u32 s4, s26, 0x1d780200
	s_addc_u32 s5, s27, 0
	v_readlane_b32 s17, v252, 1
	v_writelane_b32 v252, s4, 43
	v_mbcnt_hi_u32_b32 v201, -1, v0
	v_writelane_b32 v255, s34, 0
	v_writelane_b32 v252, s5, 44
	s_add_u32 s4, s26, 0x1d780400
	s_addc_u32 s5, s27, 0
	v_writelane_b32 v252, s4, 45
	v_and_b32_e32 v202, 64, v201
	v_writelane_b32 v255, s35, 1
	v_writelane_b32 v252, s5, 46
	s_add_u32 s4, s26, 0x1d780500
	s_addc_u32 s5, s27, 0
	v_writelane_b32 v252, s4, 47
	v_mov_b32_e32 v167, 0x358637bd
	v_mov_b32_e32 v196, 1
	v_writelane_b32 v252, s5, 48
	s_add_u32 s4, s26, 0x1d780600
	s_addc_u32 s5, s27, 0
	v_writelane_b32 v252, s4, 49
	v_mov_b32_e32 v197, 0x3000
	v_mov_b32_e32 v198, 0x6000
	v_writelane_b32 v252, s5, 50
	s_add_u32 s4, s26, 0x1d780700
	s_addc_u32 s5, s27, 0
	v_writelane_b32 v252, s4, 51
	v_mov_b32_e32 v199, 0x9000
	v_mov_b32_e32 v200, 0x3ecc95a3
	v_writelane_b32 v252, s5, 52
	s_add_u32 s4, s26, 0x1d780800
	s_addc_u32 s5, s27, 0
	v_writelane_b32 v252, s4, 53
	v_add_u32_e32 v203, 64, v202
	v_xor_b32_e32 v204, 1, v201
	v_writelane_b32 v252, s5, 54
	s_add_u32 s4, s26, 0x1d780900
	s_addc_u32 s5, s27, 0
	v_writelane_b32 v252, s4, 55
	v_xor_b32_e32 v205, 2, v201
	v_xor_b32_e32 v206, 4, v201
	v_writelane_b32 v252, s5, 56
	s_add_u32 s4, s26, 0x1d780a00
	s_addc_u32 s5, s27, 0
	v_writelane_b32 v252, s4, 57
	v_xor_b32_e32 v207, 8, v201
	v_xor_b32_e32 v208, 16, v201
	v_writelane_b32 v252, s5, 58
	s_add_u32 s4, s26, 0x1d780b00
	s_addc_u32 s5, s27, 0
	v_writelane_b32 v252, s4, 59
	v_xor_b32_e32 v209, 32, v201
	v_mov_b32_e32 v210, 0xff800000
	v_writelane_b32 v252, s5, 60
	s_add_u32 s4, s26, 0x1d780c00
	s_addc_u32 s5, s27, 0
	v_writelane_b32 v252, s4, 61
	v_mov_b32_e32 v168, 0x3f317218
	v_mov_b32_e32 v211, 0x7f800000
	v_writelane_b32 v252, s5, 62
	s_add_u32 s4, s26, 0x1d780d00
	s_addc_u32 s5, s27, 0
	v_writelane_b32 v252, s4, 63
	v_mov_b32_e32 v212, 0x7fc00000
	v_mov_b32_e32 v213, 0x1100
	v_writelane_b32 v253, s5, 0
	s_add_u32 s4, s26, 0x1d780e00
	s_addc_u32 s5, s27, 0
	v_writelane_b32 v253, s4, 1
	v_mov_b64_e32 v[174:175], 0x21f
	s_mov_b32 s10, s11
	v_writelane_b32 v253, s5, 2
	s_add_u32 s4, s26, 0x1d780f00
	s_addc_u32 s5, s27, 0
	v_writelane_b32 v253, s4, 3
	s_movk_i32 s33, 0x4600
	s_movk_i32 s74, 0x90
	v_writelane_b32 v253, s5, 4
	s_add_u32 s4, s26, 0x1d781000
	s_addc_u32 s5, s27, 0
	v_writelane_b32 v253, s4, 5
	s_nop 1
	v_writelane_b32 v253, s5, 6
	s_add_u32 s4, s26, 0x1d781100
	s_addc_u32 s5, s27, 0
	v_writelane_b32 v253, s4, 7
	s_nop 1
	v_writelane_b32 v253, s5, 8
	s_add_u32 s4, s26, 0x1d781200
	s_addc_u32 s5, s27, 0
	v_writelane_b32 v253, s4, 9
	s_nop 1
	v_writelane_b32 v253, s5, 10
	s_add_u32 s4, s26, 0x1d781300
	s_addc_u32 s5, s27, 0
	v_writelane_b32 v253, s4, 11
	s_cmp_eq_u32 s3, 15
	s_nop 0
	v_writelane_b32 v253, s5, 12
	s_cselect_b64 s[4:5], -1, 0
	v_writelane_b32 v253, s4, 13
	s_cmp_eq_u32 s3, 14
	s_nop 0
	v_writelane_b32 v253, s5, 14
	s_cselect_b64 s[4:5], -1, 0
	v_writelane_b32 v253, s4, 15
	s_cmp_eq_u32 s3, 13
	s_nop 0
	v_writelane_b32 v253, s5, 16
	s_cselect_b64 s[4:5], -1, 0
	v_writelane_b32 v253, s4, 17
	s_cmp_eq_u32 s3, 12
	s_nop 0
	v_writelane_b32 v253, s5, 18
	s_cselect_b64 s[4:5], -1, 0
	v_writelane_b32 v253, s4, 19
	s_cmp_eq_u32 s3, 11
	s_nop 0
	v_writelane_b32 v253, s5, 20
	s_cselect_b64 s[4:5], -1, 0
	v_writelane_b32 v253, s4, 21
	s_cmp_eq_u32 s3, 10
	s_nop 0
	v_writelane_b32 v253, s5, 22
	s_cselect_b64 s[4:5], -1, 0
	v_writelane_b32 v253, s4, 23
	s_cmp_eq_u32 s3, 9
	s_nop 0
	v_writelane_b32 v253, s5, 24
	s_cselect_b64 s[4:5], -1, 0
	v_writelane_b32 v253, s4, 25
	s_cmp_eq_u32 s3, 8
	s_nop 0
	v_writelane_b32 v253, s5, 26
	s_cselect_b64 s[4:5], -1, 0
	v_writelane_b32 v253, s4, 27
	s_cmp_eq_u32 s3, 7
	s_nop 0
	v_writelane_b32 v253, s5, 28
	s_cselect_b64 s[4:5], -1, 0
	v_writelane_b32 v253, s4, 29
	s_cmp_eq_u32 s3, 6
	s_nop 0
	v_writelane_b32 v253, s5, 30
	s_cselect_b64 s[4:5], -1, 0
	v_writelane_b32 v253, s4, 31
	s_cmp_eq_u32 s3, 5
	s_nop 0
	v_writelane_b32 v253, s5, 32
	s_cselect_b64 s[4:5], -1, 0
	v_writelane_b32 v253, s4, 33
	s_cmp_eq_u32 s3, 4
	s_nop 0
	v_writelane_b32 v253, s5, 34
	s_cselect_b64 s[4:5], -1, 0
	v_writelane_b32 v253, s4, 35
	s_cmp_eq_u32 s3, 3
	s_nop 0
	v_writelane_b32 v253, s5, 36
	s_cselect_b64 s[4:5], -1, 0
	v_writelane_b32 v253, s4, 37
	s_cmp_eq_u32 s3, 2
	s_nop 0
	v_writelane_b32 v253, s5, 38
	s_cselect_b64 s[4:5], -1, 0
	v_writelane_b32 v253, s4, 39
	s_cmp_eq_u32 s3, 1
	s_nop 0
	v_writelane_b32 v253, s5, 40
	s_cselect_b64 s[4:5], -1, 0
	v_writelane_b32 v253, s4, 41
	s_cmp_eq_u32 s3, 0
	s_nop 0
	v_writelane_b32 v253, s5, 42
	s_cselect_b64 s[4:5], -1, 0
	s_lshl_b32 s3, s8, 2
	s_add_u32 s0, s0, s3
	v_writelane_b32 v253, s4, 43
	s_addc_u32 s1, s1, 0
	s_nop 0
	v_writelane_b32 v253, s5, 44
	s_add_u32 s4, s0, 0x1400
	s_addc_u32 s5, s1, 0
	v_writelane_b32 v253, s4, 45
	s_add_u32 s0, s0, 0x2400
	s_addc_u32 s1, s1, 0
	v_writelane_b32 v253, s5, 46
	v_writelane_b32 v253, s0, 47
	s_nop 1
	v_writelane_b32 v253, s1, 48
	s_add_u32 s0, s26, 0x1d783400
;     __device__ __forceinline__ const char* Ap(int part) const { return (const char*)A0 + (long)(part == 1) * ((const char*)A1 - (const char*)A0) + (long)(part == 2) * ((const char*)A2 - (const char*)A0); }
;     __device__ __forceinline__ const char* Bp(int part) const { return (const char*)B0 + (long)(part == 1) * ((const char*)B1 - (const char*)B0) + (long)(part == 2) * ((const char*)B2 - (const char*)B0); }
;     __device__ __forceinline__ bool next(int i, Unit& u) const {
;         const int r = i / np; u.part = i - r * np;
;         long L = (long)r * G + c;
;         if (L >= split_from) { const long Ls = L - split_from; if (Ls >= 2L * (nwg - split_from)) return false; L = split_from + (Ls >> 1); u.part = 1 + (int)(Ls & 1); }
;         if (L >= nwg) return false;
;         int wgid = (int)L; { const int q = nwg / NXCD, rr = nwg % NXCD, xcd = wgid % NXCD, off = wgid / NXCD; wgid = (xcd < rr ? xcd * (q + 1) : rr * (q + 1) + (xcd - rr) * q) + off; }
;         const int nig = WGM * nN, gid = wgid / nig, fm = gid * WGM, gsz = (nM - fm) < WGM ? (nM - fm) : WGM;
;         u.pm = fm + ((wgid % nig) % gsz); u.pn = (wgid % nig) / gsz; return true;
; template <class Epi, bool GS = false>
; __device__ __forceinline__ void gemm_phase(LAS unsigned char* lds, const Gemm g, const StaticOrder& S, const Epi& E, const int tid) {
;     ...
;     const char* cA = g.Ap(cur.part) + (size_t)cur.pm * tstepA; const char* cB = g.Bp(cur.part) + (size_t)cur.pn * tstepB;
	s_addc_u32 s1, s27, 0
	v_writelane_b32 v253, s0, 49
	s_nop 1
	v_writelane_b32 v253, s1, 50
	s_add_u32 s0, s26, 0x1d783500
	s_addc_u32 s1, s27, 0
	v_writelane_b32 v253, s0, 51
	s_ashr_i32 s53, s52, 31
	s_lshl_b32 s36, s16, 9
	v_writelane_b32 v253, s1, 52
	s_ashr_i32 s0, s16, 31
	v_writelane_b32 v253, s0, 53
	s_add_u32 s0, s24, 0xef60000
	s_addc_u32 s1, s25, 0
	v_writelane_b32 v253, s0, 54
	v_writelane_b32 v255, s36, 2
	s_nop 0
	v_writelane_b32 v253, s1, 55
	s_add_u32 s0, s24, 0xf760000
	s_addc_u32 s1, s25, 0
	v_writelane_b32 v253, s0, 56
	s_nop 1
	v_writelane_b32 v253, s1, 57
	s_add_u32 s0, s24, 0xeb60000
	s_addc_u32 s1, s25, 0
	v_writelane_b32 v253, s0, 58
	s_nop 1
	v_writelane_b32 v253, s1, 59
	s_add_u32 s0, s24, 0xf360000
	s_addc_u32 s1, s25, 0
	v_writelane_b32 v253, s0, 60
	s_cmp_lt_i32 s2, 0x8800
	s_nop 0
	v_writelane_b32 v253, s1, 61
	s_cselect_b64 s[0:1], -1, 0
	v_writelane_b32 v253, s0, 62
	s_cmpk_lt_i32 s52, 0xbb0
	s_nop 0
	v_writelane_b32 v253, s1, 63
	s_cselect_b64 s[0:1], -1, 0
	v_writelane_b32 v254, s0, 0
	s_nop 1
	v_writelane_b32 v254, s1, 1
	s_lshr_b32 s0, s53, 29
	s_add_i32 s0, s52, s0
	s_ashr_i32 s7, s0, 3
	s_and_b32 s0, s0, -8
	s_sub_i32 s8, s52, s0
	s_cmpk_lt_i32 s52, 0x220
	s_cselect_b64 s[0:1], -1, 0
	v_writelane_b32 v254, s0, 2
	s_nop 1
	v_writelane_b32 v254, s1, 3
	s_lshr_b32 s0, s8, 31
	v_writelane_b32 v254, s0, 4
	s_cmp_lt_i32 s8, 0
	s_movk_i32 s0, 0x177
	s_cselect_b32 s0, s0, 0x176
	s_mul_i32 s0, s8, s0
	s_movk_i32 s1, 0x45
	s_cselect_b32 s3, s1, 0x44
	s_add_i32 s0, s0, s7
	s_mul_hi_i32 s1, s0, 0x2e8ba2e9
	s_lshr_b32 s4, s1, 31
	s_ashr_i32 s1, s1, 5
	s_add_i32 s1, s1, s4
	s_mul_i32 s4, s1, 0xb0
	s_sub_i32 s0, s0, s4
	s_bfe_u32 s4, s0, 0x3001c
	s_add_i32 s4, s0, s4
	s_and_b32 s5, s4, 0xfff8
	s_sub_i32 s0, s0, s5
	s_lshl_b32 s1, s1, 3
	s_sext_i32_i16 s4, s4
	s_sext_i32_i16 s0, s0
	s_add_i32 s14, s1, s0
	s_ashr_i32 s0, s4, 3
	v_writelane_b32 v254, s0, 5
	s_lshr_b32 s0, s4, 3
	s_bfe_i64 s[0:1], s[0:1], 0x100000
	s_lshl_b64 s[0:1], s[0:1], 19
	v_writelane_b32 v254, s0, 6
	s_ashr_i32 s15, s14, 31
	s_nop 0
	v_writelane_b32 v254, s1, 7
	s_mov_b32 s0, s14
	v_writelane_b32 v254, s0, 8
	s_nop 1
	v_writelane_b32 v254, s1, 9
	s_add_i32 s0, s14, 0x48
	s_add_i32 s1, s14, 0xffffffc0
	s_cmp_lt_i32 s14, 64
	s_cselect_b32 s0, s0, s1
	s_ashr_i32 s1, s0, 31
	s_lshl_b64 s[0:1], s[0:1], 19
	s_add_u32 s0, s12, s0
	s_addc_u32 s1, s13, s1
	s_add_u32 s4, s0, 0x40000
	v_writelane_b32 v254, s0, 10
	s_addc_u32 s5, s1, 0
	s_nop 0
	v_writelane_b32 v254, s1, 11
	s_mul_i32 s0, s8, s3
	s_add_i32 s0, s0, s7
	s_ashr_i32 s1, s0, 31
	s_lshr_b32 s1, s1, 27
	s_add_i32 s1, s0, s1
	s_and_b32 s3, s1, 0xffe0
	s_sub_i32 s0, s0, s3
	s_bfe_i32 s3, s0, 0x80000
	s_bfe_u32 s3, s3, 0x3000c
	v_writelane_b32 v254, s4, 12
	s_add_i32 s3, s0, s3
	s_ashr_i32 s1, s1, 5
	v_writelane_b32 v254, s5, 13
	s_and_b32 s4, s3, 0xf8
	s_sub_i32 s0, s0, s4
	s_lshl_b32 s1, s1, 3
	s_sext_i32_i8 s0, s0
	s_add_i32 s1, s1, s0
	s_bfe_i32 s0, s3, 0x80000
	v_writelane_b32 v254, s8, 14
	s_sext_i32_i16 s0, s0
	v_writelane_b32 v254, s7, 15
	s_ashr_i32 s0, s0, 3
	v_writelane_b32 v254, s0, 16
	s_add_i32 s0, s52, 0x7fffff00
	v_writelane_b32 v254, s0, 17
	s_mul_hi_i32 s0, s1, 0x160000
	v_writelane_b32 v254, s1, 18
	s_mul_i32 s1, s1, 0x160000
	s_add_u32 s4, s18, s1
	s_addc_u32 s5, s19, s0
	s_add_u32 s0, s4, 0xb0000
	v_writelane_b32 v254, s4, 19
	s_addc_u32 s1, s5, 0
	s_ashr_i32 s3, s2, 31
	v_writelane_b32 v254, s5, 20
	v_writelane_b32 v254, s0, 21
	s_mov_b64 s[4:5], -1
	s_nop 0
	v_writelane_b32 v254, s1, 22
	s_lshl_b64 s[0:1], s[2:3], 11
	s_add_u32 s0, s26, s0
	s_addc_u32 s1, s27, s1
	v_writelane_b32 v254, s0, 23
	s_ashr_i32 s7, s6, 31
	s_nop 0
	v_writelane_b32 v254, s1, 24
	v_writelane_b32 v254, s2, 25
	v_readlane_b32 s0, v252, 4
	s_add_i32 s0, s2, s0
	v_writelane_b32 v254, s3, 26
	s_ashr_i32 s1, s0, 31
	v_writelane_b32 v254, s6, 27
	s_lshl_b64 s[0:1], s[0:1], 11
	s_lshl_b64 s[2:3], s[6:7], 11
	v_writelane_b32 v254, s7, 28
	v_writelane_b32 v254, s2, 29
	s_add_u32 s0, s26, s0
	s_addc_u32 s1, s27, s1
	v_writelane_b32 v254, s3, 30
	v_writelane_b32 v254, s0, 31
	s_nop 1
	v_writelane_b32 v254, s1, 32
	s_mul_i32 s0, s17, s16
	s_mul_i32 s0, s0, s51
	v_writelane_b32 v254, s0, 33
	s_lshl_b32 s0, s52, 7
	v_writelane_b32 v254, s0, 34
	s_lshl_b32 s0, s16, 7
	v_writelane_b32 v254, s0, 35
	s_lshl_b32 s0, s52, 5
	v_writelane_b32 v254, s0, 36
	s_lshl_b32 s0, s16, 5
	v_writelane_b32 v254, s0, 37
	v_writelane_b32 v254, s52, 38
	s_add_i32 s0, s52, 0xffffff00
	s_nop 0
	v_writelane_b32 v254, s53, 39
	v_writelane_b32 v254, s0, 40
	s_add_i32 s0, 0, 0x22fc0
	v_writelane_b32 v254, s0, 41
	s_add_i32 s0, 0, 0x22fc4
	v_writelane_b32 v254, s0, 42
	s_add_i32 s0, 0, 0xd000
	v_writelane_b32 v254, s0, 43
	s_add_i32 s0, 0, 0x15c00
	v_writelane_b32 v254, s0, 44
	s_add_i32 s0, 0, 0x11800
	v_writelane_b32 v254, s0, 45
	s_add_i32 s0, 0, 0x1c73c
	v_writelane_b32 v254, s0, 46
	s_add_i32 s0, 0, 0x1f040
	v_writelane_b32 v254, s0, 47
	v_writelane_b32 v254, s76, 48
	s_mov_b64 s[0:1], 0x80
	s_nop 0
	v_writelane_b32 v254, s77, 49
	v_writelane_b32 v254, s78, 50
	v_writelane_b32 v254, s79, 51
	v_writelane_b32 v254, s80, 52
	v_writelane_b32 v254, s81, 53
	v_writelane_b32 v254, s82, 54
	v_writelane_b32 v254, s83, 55
	v_writelane_b32 v254, s84, 56
	v_writelane_b32 v254, s85, 57
	v_writelane_b32 v254, s86, 58
	v_writelane_b32 v254, s87, 59
	v_writelane_b32 v254, s88, 60
	v_writelane_b32 v254, s89, 61
	v_writelane_b32 v254, s90, 62
	v_writelane_b32 v254, s91, 63
	s_branch .LBB0_136

; __device__ __forceinline__ void norm_mod_rows(const float* __restrict__ xp, const float* __restrict__ xs, const float* __restrict__ gvec, const float* __restrict__ mod, int ch_shift, int ch_scale, ...
;     for (int r0 = gw; r0 < nrows; r0 += 2 * NGW) {
;         const int r1 = r0 + NGW; const bool two = r1 < nrows;
;         const int gr0 = row_base + r0, gr1 = row_base + (two ? r1 : r0);
;         const float* xrow0 = gr0 < MP ? xp + (size_t)gr0 * DM : xs + (size_t)(gr0 - MP) * DM;
;         const float* xrow1 = gr1 < MP ? xp + (size_t)gr1 * DM : xs + (size_t)(gr1 - MP) * DM;
;         f32x4 v0[4], v1[4]; float s0 = 0.f, s1 = 0.f;
; #pragma unroll
;         for (int j = 0; j < 4; ++j) { v0[j] = ((const f32x4*)xrow0)[lane + 64 * j]; v1[j] = ((const f32x4*)xrow1)[lane + 64 * j]; }
; #pragma unroll
;         for (int j = 0; j < 4; ++j) { s0 += (v0[j][0] * v0[j][0] + v0[j][1] * v0[j][1]) + (v0[j][2] * v0[j][2] + v0[j][3] * v0[j][3]);
;                                       s1 += (v1[j][0] * v1[j][0] + v1[j][1] * v1[j][1]) + (v1[j][2] * v1[j][2] + v1[j][3] * v1[j][3]); }
;         const float rstd0 = rsqrtf(wave_sum(s0) * (1.f / DM) + EPS), rstd1 = rsqrtf(wave_sum(s1) * (1.f / DM) + EPS);
; #pragma unroll
;         for (int q = 0; q < 2; ++q) {
;             if (q == 1 && !two) break;
;             const int gr = q ? gr1 : gr0, r = q ? r1 : r0; const float rstd = q ? rstd1 : rstd0;
;             const int seq = gr < MP ? (gr >> 11) : NPB + ((gr - MP) >> 6);
;             const float* mrow = mod + (size_t)seq * (6 * DM);
;             u32x2* o8 = (u32x2*)(H + (size_t)r * DM);
;             f32x4 gq[4], scq[4], shq[4];
; #pragma unroll
;             for (int j = 0; j < 4; ++j) { const int ci = lane + 64 * j;
;                 gq[j] = ((const f32x4*)gvec)[ci]; scq[j] = ((const f32x4*)(mrow + ch_scale * DM))[ci]; shq[j] = ((const f32x4*)(mrow + ch_shift * DM))[ci]; }
.LBB0_720:
	v_readlane_b32 s3, v255, 31
	v_readlane_b32 s4, v252, 2
	s_cmp_eq_u32 s3, 0
	s_cbranch_scc1 .Lp7a_skip
	s_cmp_lt_u32 s4, 0x8000
	s_cbranch_scc1 .Lp7a_skip
	v_and_b32_e32 v216, 63, v166
	v_lshlrev_b32_e32 v80, 4, v216
	v_readlane_b32 s40, v255, 5
	v_readlane_b32 s41, v255, 6
	v_readlane_b32 s42, v252, 13
	v_readlane_b32 s43, v252, 14
	s_add_u32 s40, s42, s40
	s_addc_u32 s41, s43, s41
	s_nop 4
	global_load_dwordx4 v[96:99], v80, s[40:41]
	global_load_dwordx4 v[100:103], v80, s[40:41] offset:1024
	global_load_dwordx4 v[104:107], v80, s[40:41] offset:2048
	global_load_dwordx4 v[108:111], v80, s[40:41] offset:3072
	v_add_u32_e32 v81, 0x1000, v80
	v_add_u32_e32 v82, 0x3000, v80
	v_add_u32_e32 v83, 0x4000, v80
	v_lshlrev_b32_e32 v0, 3, v216
	v_readlane_b32 s3, v254, 25
	s_movk_i32 s5, 0x600
	s_add_i32 s3, s3, 0xfffffe00
	s_movk_i32 s4, 0x2000
	s_mov_b32 s8, 0
	s_cmp_ge_i32 s3, s4
	s_cbranch_scc1 .Lp7a_skip
.Lnorm_loop_p7a:
	s_lshl_b32 s9, s3, 1
	s_add_i32 s28, s9, s8
	s_lshl_b32 s46, s9, 11
	s_add_i32 s46, s46, 0x2400000
	s_add_u32 s44, s12, s46
	s_addc_u32 s45, s13, 0
	s_add_i32 s9, s28, 0xffff8000
	s_ashr_i32 s46, s28, 11
	s_lshr_b32 s42, s9, 6
	s_add_i32 s42, s42, 16
	s_cmp_lt_i32 s28, 0x8000
	s_cselect_b32 s40, s24, s24
	s_cselect_b32 s41, s25, s25
	s_cselect_b32 s9, s28, s9
	s_cselect_b32 s46, s46, s42
	s_lshl_b32 s9, s9, 12
	s_add_u32 s40, s40, s9
	s_addc_u32 s41, s41, 0
	s_mul_i32 s46, s46, 0x6000
	v_readlane_b32 s42, v255, 24
	v_readlane_b32 s43, v255, 26
	s_add_u32 s42, s42, s46
	s_addc_u32 s43, s43, 0
	global_load_dwordx4 v[216:219], v80, s[40:41]
	global_load_dwordx4 v[220:223], v80, s[40:41] offset:1024
	global_load_dwordx4 v[224:227], v80, s[40:41] offset:2048
	global_load_dwordx4 v[228:231], v80, s[40:41] offset:3072
	global_load_dwordx4 v[232:235], v81, s[40:41]
	global_load_dwordx4 v[236:239], v81, s[40:41] offset:1024
	global_load_dwordx4 v[240:243], v81, s[40:41] offset:2048
	global_load_dwordx4 v[244:247], v81, s[40:41] offset:3072
	global_load_dwordx4 v[62:65], v83, s[42:43]
	global_load_dwordx4 v[66:69], v83, s[42:43] offset:1024
	global_load_dwordx4 v[70:73], v83, s[42:43] offset:2048
	global_load_dwordx4 v[74:77], v83, s[42:43] offset:3072
	global_load_dwordx4 v[176:179], v82, s[42:43]
	global_load_dwordx4 v[180:183], v82, s[42:43] offset:1024
	global_load_dwordx4 v[184:187], v82, s[42:43] offset:2048
	global_load_dwordx4 v[188:191], v82, s[42:43] offset:3072
	s_waitcnt vmcnt(15)
	v_pk_mul_f32 v[78:79], v[216:217], v[216:217]
	v_pk_fma_f32 v[78:79], v[218:219], v[218:219], v[78:79]
	s_waitcnt vmcnt(14)
	v_pk_fma_f32 v[78:79], v[220:221], v[220:221], v[78:79]
	v_pk_fma_f32 v[78:79], v[222:223], v[222:223], v[78:79]
	s_waitcnt vmcnt(13)
	v_pk_fma_f32 v[78:79], v[224:225], v[224:225], v[78:79]
	v_pk_fma_f32 v[78:79], v[226:227], v[226:227], v[78:79]
	s_waitcnt vmcnt(12)
	v_pk_fma_f32 v[78:79], v[228:229], v[228:229], v[78:79]
	v_pk_fma_f32 v[78:79], v[230:231], v[230:231], v[78:79]
	s_waitcnt vmcnt(11)
	v_pk_mul_f32 v[84:85], v[232:233], v[232:233]
	v_pk_fma_f32 v[84:85], v[234:235], v[234:235], v[84:85]
	s_waitcnt vmcnt(10)
	v_pk_fma_f32 v[84:85], v[236:237], v[236:237], v[84:85]
	v_pk_fma_f32 v[84:85], v[238:239], v[238:239], v[84:85]
	s_waitcnt vmcnt(9)
	v_pk_fma_f32 v[84:85], v[240:241], v[240:241], v[84:85]
	v_pk_fma_f32 v[84:85], v[242:243], v[242:243], v[84:85]
	s_waitcnt vmcnt(8)
	v_pk_fma_f32 v[84:85], v[244:245], v[244:245], v[84:85]
	v_pk_fma_f32 v[84:85], v[246:247], v[246:247], v[84:85]
	s_nop 0
	v_add_f32_e32 v78, v78, v79
	v_add_f32_e32 v84, v84, v85
	s_nop 1
	v_add_f32_dpp v78, v78, v78 quad_perm:[1,0,3,2] row_mask:0xf bank_mask:0xf bound_ctrl:1
	v_add_f32_dpp v84, v84, v84 quad_perm:[1,0,3,2] row_mask:0xf bank_mask:0xf bound_ctrl:1
	s_nop 1
	v_add_f32_dpp v78, v78, v78 quad_perm:[2,3,0,1] row_mask:0xf bank_mask:0xf bound_ctrl:1
	v_add_f32_dpp v84, v84, v84 quad_perm:[2,3,0,1] row_mask:0xf bank_mask:0xf bound_ctrl:1
	s_nop 1
	v_add_f32_dpp v78, v78, v78 row_half_mirror row_mask:0xf bank_mask:0xf bound_ctrl:1
	v_add_f32_dpp v84, v84, v84 row_half_mirror row_mask:0xf bank_mask:0xf bound_ctrl:1
	s_nop 1
	v_add_f32_dpp v78, v78, v78 row_mirror row_mask:0xf bank_mask:0xf bound_ctrl:1
	v_add_f32_dpp v84, v84, v84 row_mirror row_mask:0xf bank_mask:0xf bound_ctrl:1
	s_nop 1
	v_add_f32_dpp v78, v78, v78 row_bcast:15 row_mask:0xa bank_mask:0xf
	v_add_f32_dpp v84, v84, v84 row_bcast:15 row_mask:0xa bank_mask:0xf
	s_nop 1
	v_add_f32_dpp v78, v78, v78 row_bcast:31 row_mask:0xc bank_mask:0xf
	v_add_f32_dpp v84, v84, v84 row_bcast:31 row_mask:0xc bank_mask:0xf
	s_nop 1
	v_readlane_b32 s9, v78, 63
	v_readlane_b32 s28, v84, 63
	s_nop 2
	v_mov_b32_e32 v86, s9
	v_mov_b32_e32 v88, s28
	v_fmamk_f32 v86, v86, 0x3a800000, v167
	v_fmamk_f32 v88, v88, 0x3a800000, v167
	v_rsq_f32_e32 v86, v86
	v_rsq_f32_e32 v88, v88
	s_waitcnt vmcnt(4)
; __device__ __forceinline__ unsigned pk2(float lo, float hi) { unsigned r; asm("v_cvt_pk_bf16_f32 %0, %1, %2" : "=v"(r) : "v"(lo), "v"(hi)); return r; }
; __device__ __forceinline__ void norm_mod_rows(const float* __restrict__ xp, const float* __restrict__ xs, const float* __restrict__ gvec, const float* __restrict__ mod, int ch_shift, int ch_scale, ...
;     ...
; #pragma unroll
;             for (int j = 0; j < 4; ++j) { const int ci = lane + 64 * j;
;                 const f32x4 y = ((q ? v1[j] : v0[j]) * rstd) * gq[j] * (scq[j] + 1.f) + shq[j];
;                 u32x2 w; w.x = pk2(y[0], y[1]); w.y = pk2(y[2], y[3]); o8[ci] = w; }
;         }
	v_pk_add_f32 v[62:63], v[62:63], 1.0 op_sel_hi:[1,0]
	v_pk_add_f32 v[64:65], v[64:65], 1.0 op_sel_hi:[1,0]
	v_pk_add_f32 v[66:67], v[66:67], 1.0 op_sel_hi:[1,0]
	v_pk_add_f32 v[68:69], v[68:69], 1.0 op_sel_hi:[1,0]
	v_pk_add_f32 v[70:71], v[70:71], 1.0 op_sel_hi:[1,0]
	v_pk_add_f32 v[72:73], v[72:73], 1.0 op_sel_hi:[1,0]
	v_pk_add_f32 v[74:75], v[74:75], 1.0 op_sel_hi:[1,0]
	v_pk_add_f32 v[76:77], v[76:77], 1.0 op_sel_hi:[1,0]
	s_waitcnt vmcnt(0)
	v_pk_mul_f32 v[216:217], v[216:217], v[86:87] op_sel_hi:[1,0]
	v_pk_mul_f32 v[218:219], v[218:219], v[86:87] op_sel_hi:[1,0]
	v_pk_mul_f32 v[220:221], v[220:221], v[86:87] op_sel_hi:[1,0]
	v_pk_mul_f32 v[222:223], v[222:223], v[86:87] op_sel_hi:[1,0]
	v_pk_mul_f32 v[224:225], v[224:225], v[86:87] op_sel_hi:[1,0]
	v_pk_mul_f32 v[226:227], v[226:227], v[86:87] op_sel_hi:[1,0]
	v_pk_mul_f32 v[228:229], v[228:229], v[86:87] op_sel_hi:[1,0]
	v_pk_mul_f32 v[230:231], v[230:231], v[86:87] op_sel_hi:[1,0]
	v_pk_mul_f32 v[216:217], v[96:97], v[216:217]
	v_pk_mul_f32 v[218:219], v[98:99], v[218:219]
	v_pk_mul_f32 v[220:221], v[100:101], v[220:221]
	v_pk_mul_f32 v[222:223], v[102:103], v[222:223]
	v_pk_mul_f32 v[224:225], v[104:105], v[224:225]
	v_pk_mul_f32 v[226:227], v[106:107], v[226:227]
	v_pk_mul_f32 v[228:229], v[108:109], v[228:229]
	v_pk_mul_f32 v[230:231], v[110:111], v[230:231]
	v_pk_fma_f32 v[216:217], v[62:63], v[216:217], v[176:177]
	v_pk_fma_f32 v[218:219], v[64:65], v[218:219], v[178:179]
	v_pk_fma_f32 v[220:221], v[66:67], v[220:221], v[180:181]
	v_pk_fma_f32 v[222:223], v[68:69], v[222:223], v[182:183]
	v_pk_fma_f32 v[224:225], v[70:71], v[224:225], v[184:185]
	v_pk_fma_f32 v[226:227], v[72:73], v[226:227], v[186:187]
	v_pk_fma_f32 v[228:229], v[74:75], v[228:229], v[188:189]
	v_pk_fma_f32 v[230:231], v[76:77], v[230:231], v[190:191]
	v_cvt_pk_bf16_f32 v216, v216, v217
	v_cvt_pk_bf16_f32 v217, v218, v219
	v_cvt_pk_bf16_f32 v220, v220, v221
	v_cvt_pk_bf16_f32 v221, v222, v223
	v_cvt_pk_bf16_f32 v224, v224, v225
	v_cvt_pk_bf16_f32 v225, v226, v227
	v_cvt_pk_bf16_f32 v228, v228, v229
	v_cvt_pk_bf16_f32 v229, v230, v231
	global_store_dwordx2 v0, v[216:217], s[44:45]
	global_store_dwordx2 v0, v[220:221], s[44:45] offset:512
	global_store_dwordx2 v0, v[224:225], s[44:45] offset:1024
	global_store_dwordx2 v0, v[228:229], s[44:45] offset:1536
	v_pk_mul_f32 v[232:233], v[232:233], v[88:89] op_sel_hi:[1,0]
	v_pk_mul_f32 v[234:235], v[234:235], v[88:89] op_sel_hi:[1,0]
	v_pk_mul_f32 v[236:237], v[236:237], v[88:89] op_sel_hi:[1,0]
	v_pk_mul_f32 v[238:239], v[238:239], v[88:89] op_sel_hi:[1,0]
	v_pk_mul_f32 v[240:241], v[240:241], v[88:89] op_sel_hi:[1,0]
	v_pk_mul_f32 v[242:243], v[242:243], v[88:89] op_sel_hi:[1,0]
	v_pk_mul_f32 v[244:245], v[244:245], v[88:89] op_sel_hi:[1,0]
	v_pk_mul_f32 v[246:247], v[246:247], v[88:89] op_sel_hi:[1,0]
	v_pk_mul_f32 v[232:233], v[96:97], v[232:233]
	v_pk_mul_f32 v[234:235], v[98:99], v[234:235]
	v_pk_mul_f32 v[236:237], v[100:101], v[236:237]
	v_pk_mul_f32 v[238:239], v[102:103], v[238:239]
	v_pk_mul_f32 v[240:241], v[104:105], v[240:241]
	v_pk_mul_f32 v[242:243], v[106:107], v[242:243]
	v_pk_mul_f32 v[244:245], v[108:109], v[244:245]
	v_pk_mul_f32 v[246:247], v[110:111], v[246:247]
	v_pk_fma_f32 v[232:233], v[62:63], v[232:233], v[176:177]
	v_pk_fma_f32 v[234:235], v[64:65], v[234:235], v[178:179]
	v_pk_fma_f32 v[236:237], v[66:67], v[236:237], v[180:181]
	v_pk_fma_f32 v[238:239], v[68:69], v[238:239], v[182:183]
	v_pk_fma_f32 v[240:241], v[70:71], v[240:241], v[184:185]
	v_pk_fma_f32 v[242:243], v[72:73], v[242:243], v[186:187]
	v_pk_fma_f32 v[244:245], v[74:75], v[244:245], v[188:189]
	v_pk_fma_f32 v[246:247], v[76:77], v[246:247], v[190:191]
	v_cvt_pk_bf16_f32 v232, v232, v233
	v_cvt_pk_bf16_f32 v233, v234, v235
	v_cvt_pk_bf16_f32 v236, v236, v237
	v_cvt_pk_bf16_f32 v237, v238, v239
	v_cvt_pk_bf16_f32 v240, v240, v241
	v_cvt_pk_bf16_f32 v241, v242, v243
	v_cvt_pk_bf16_f32 v244, v244, v245
	v_cvt_pk_bf16_f32 v245, v246, v247
	global_store_dwordx2 v0, v[232:233], s[44:45] offset:2048
	global_store_dwordx2 v0, v[236:237], s[44:45] offset:2560
	global_store_dwordx2 v0, v[240:241], s[44:45] offset:3072
	global_store_dwordx2 v0, v[244:245], s[44:45] offset:3584
	s_add_i32 s3, s3, s5
	s_cmp_lt_i32 s3, s4
	s_cbranch_scc1 .Lnorm_loop_p7a

; __device__ __forceinline__ void norm_mod_rows(const float* __restrict__ xp, const float* __restrict__ xs, const float* __restrict__ gvec, const float* __restrict__ mod, int ch_shift, int ch_scale, ...
;     for (int r0 = gw; r0 < nrows; r0 += 2 * NGW) {
;         const int r1 = r0 + NGW; const bool two = r1 < nrows;
;         const int gr0 = row_base + r0, gr1 = row_base + (two ? r1 : r0);
;         const float* xrow0 = gr0 < MP ? xp + (size_t)gr0 * DM : xs + (size_t)(gr0 - MP) * DM;
;         const float* xrow1 = gr1 < MP ? xp + (size_t)gr1 * DM : xs + (size_t)(gr1 - MP) * DM;
;         f32x4 v0[4], v1[4]; float s0 = 0.f, s1 = 0.f;
; #pragma unroll
;         for (int j = 0; j < 4; ++j) { v0[j] = ((const f32x4*)xrow0)[lane + 64 * j]; v1[j] = ((const f32x4*)xrow1)[lane + 64 * j]; }
.LBB0_855:
	v_readlane_b32 s2, v253, 62
	v_readlane_b32 s3, v253, 63
	v_readlane_b32 s34, v255, 0
	v_mov_b32_e32 v0, v166
	s_andn2_b64 vcc, exec, s[2:3]
	v_readlane_b32 s35, v255, 1
	s_cbranch_vccnz .LBB0_860
	v_and_b32_e32 v18, 63, v166
	v_lshlrev_b32_e32 v85, 4, v18
	v_readlane_b32 s14, v255, 5
	v_readlane_b32 s15, v255, 6
	v_readlane_b32 s16, v252, 13
	v_readlane_b32 s17, v252, 14
	s_add_u32 s14, s16, s14
	s_addc_u32 s15, s17, s15
	s_nop 4
	global_load_dwordx4 v[2:5], v85, s[14:15]
	global_load_dwordx4 v[6:9], v85, s[14:15] offset:1024
	global_load_dwordx4 v[10:13], v85, s[14:15] offset:2048
	global_load_dwordx4 v[14:17], v85, s[14:15] offset:3072
	v_add_u32_e32 v86, 0x1000, v85
	v_add_u32_e32 v87, 0x3000, v85
	v_add_u32_e32 v88, 0x4000, v85
	v_lshlrev_b32_e32 v0, 3, v18
	v_readlane_b32 s3, v254, 25
	v_readlane_b32 s5, v252, 4
	s_movk_i32 s4, 0x2400
	s_movk_i32 s8, 0x4000
	s_cmp_ge_i32 s3, s4
	s_cbranch_scc1 .LBB0_860

;     __device__ __forceinline__ const char* Ap(int part) const { return (const char*)A0 + (long)(part == 1) * ((const char*)A1 - (const char*)A0) + (long)(part == 2) * ((const char*)A2 - (const char*)A0); }
;     __device__ __forceinline__ const char* Bp(int part) const { return (const char*)B0 + (long)(part == 1) * ((const char*)B1 - (const char*)B0) + (long)(part == 2) * ((const char*)B2 - (const char*)B0); }
; template <class Epi, bool GS = false>
; __device__ __forceinline__ void gemm_phase(LAS unsigned char* lds, const Gemm g, const StaticOrder& S, const Epi& E, const int tid) {
;     ...
;         const bool has_next = S.next(ui + 1, nxt);
;         const char* nA = has_next ? g.Ap(nxt.part) + (size_t)nxt.pm * tstepA : cA; const char* nB = has_next ? g.Bp(nxt.part) + (size_t)nxt.pn * tstepB : cB;
;     ...
; #pragma unroll
;         for (int a = 0; a < 2; ++a)
; #pragma unroll
;             for (int b = 0; b < 2; ++b)
; #pragma unroll
;                 for (int m = 0; m < 4; ++m)
; #pragma unroll
;                     for (int n = 0; n < 2; ++n) acc[a][b][m][n] = (f32x4){0.f, 0.f, 0.f, 0.f};
.LBB0_920:
	s_add_i32 s16, s14, 0x48
	s_add_i32 s17, s14, 0xffffffc0
	s_cmp_lt_i32 s14, 64
	s_cselect_b32 s16, s16, s17
	s_ashr_i32 s17, s16, 31
	s_lshl_b64 s[16:17], s[16:17], 19
	s_add_u32 s16, s12, s16
	s_addc_u32 s17, s13, s17
	s_and_b64 s[20:21], s[38:39], exec
	s_cselect_b32 s15, s17, s23
	s_cselect_b32 s47, s16, s22
	s_ashr_i32 s9, s8, 31
	s_lshl_b64 s[20:21], s[8:9], 19
	s_add_u32 s20, s2, s20
	s_addc_u32 s21, s3, s21
	s_and_b64 s[34:35], s[38:39], exec
	s_cselect_b32 s9, s21, s31
	s_cselect_b32 s48, s20, s30
	s_add_u32 s22, s22, 0x40080
	s_addc_u32 s23, s23, 0
	s_add_u32 s49, s30, 0x100
	v_mov_b32_e32 v2, 0
	s_addc_u32 s50, s31, 0
	s_mov_b32 s51, -2
	v_mov_b32_e32 v3, v2
	v_mov_b32_e32 v4, v2
	v_mov_b32_e32 v5, v2
	v_mov_b32_e32 v10, v2
	v_mov_b32_e32 v11, v2
	v_mov_b32_e32 v12, v2
	v_mov_b32_e32 v13, v2
	v_mov_b32_e32 v18, v2
	v_mov_b32_e32 v19, v2
	v_mov_b32_e32 v20, v2
	v_mov_b32_e32 v21, v2
	v_mov_b32_e32 v26, v2
	v_mov_b32_e32 v27, v2
	v_mov_b32_e32 v28, v2
	v_mov_b32_e32 v29, v2
	v_mov_b32_e32 v34, v2
	v_mov_b32_e32 v35, v2
	v_mov_b32_e32 v36, v2
	v_mov_b32_e32 v37, v2
	v_mov_b32_e32 v42, v2
	v_mov_b32_e32 v43, v2
	v_mov_b32_e32 v44, v2
	v_mov_b32_e32 v45, v2
	v_mov_b32_e32 v50, v2
	v_mov_b32_e32 v51, v2
	v_mov_b32_e32 v52, v2
	v_mov_b32_e32 v53, v2
	v_mov_b32_e32 v58, v2
	v_mov_b32_e32 v59, v2
	v_mov_b32_e32 v60, v2
	v_mov_b32_e32 v61, v2
	v_mov_b32_e32 v6, v2
	v_mov_b32_e32 v7, v2
	v_mov_b32_e32 v8, v2
	v_mov_b32_e32 v9, v2
	v_mov_b32_e32 v14, v2
	v_mov_b32_e32 v15, v2
	v_mov_b32_e32 v16, v2
	v_mov_b32_e32 v17, v2
	v_mov_b32_e32 v22, v2
	v_mov_b32_e32 v23, v2
	v_mov_b32_e32 v24, v2
	v_mov_b32_e32 v25, v2
	v_mov_b32_e32 v30, v2
	v_mov_b32_e32 v31, v2
	v_mov_b32_e32 v32, v2
	v_mov_b32_e32 v33, v2
	v_mov_b32_e32 v38, v2
	v_mov_b32_e32 v39, v2
	v_mov_b32_e32 v40, v2
	v_mov_b32_e32 v41, v2
	v_mov_b32_e32 v46, v2
	v_mov_b32_e32 v47, v2
	v_mov_b32_e32 v48, v2
	v_mov_b32_e32 v49, v2
	v_mov_b32_e32 v54, v2
	v_mov_b32_e32 v55, v2
	v_mov_b32_e32 v56, v2
	v_mov_b32_e32 v57, v2
	v_mov_b32_e32 v62, v2
	v_mov_b32_e32 v63, v2
	v_mov_b32_e32 v64, v2
	v_mov_b32_e32 v65, v2
	v_mov_b32_e32 v66, v2
	v_mov_b32_e32 v67, v2
	v_mov_b32_e32 v68, v2
	v_mov_b32_e32 v69, v2
	v_mov_b32_e32 v74, v2
	v_mov_b32_e32 v75, v2
	v_mov_b32_e32 v76, v2
	v_mov_b32_e32 v77, v2
	v_mov_b32_e32 v82, v2
	v_mov_b32_e32 v83, v2
	v_mov_b32_e32 v84, v2
	v_mov_b32_e32 v85, v2
	v_mov_b32_e32 v90, v2
	v_mov_b32_e32 v91, v2
	v_mov_b32_e32 v92, v2
	v_mov_b32_e32 v93, v2
	v_mov_b32_e32 v98, v2
	v_mov_b32_e32 v99, v2
	v_mov_b32_e32 v100, v2
	v_mov_b32_e32 v101, v2
	v_mov_b32_e32 v106, v2
	v_mov_b32_e32 v107, v2
	v_mov_b32_e32 v108, v2
	v_mov_b32_e32 v109, v2
	v_mov_b32_e32 v114, v2
	v_mov_b32_e32 v115, v2
	v_mov_b32_e32 v116, v2
	v_mov_b32_e32 v117, v2
	v_mov_b32_e32 v122, v2
	v_mov_b32_e32 v123, v2
	v_mov_b32_e32 v124, v2
	v_mov_b32_e32 v125, v2
	v_mov_b32_e32 v70, v2
	v_mov_b32_e32 v71, v2
	v_mov_b32_e32 v72, v2
	v_mov_b32_e32 v73, v2
	v_mov_b32_e32 v78, v2
	v_mov_b32_e32 v79, v2
	v_mov_b32_e32 v80, v2
	v_mov_b32_e32 v81, v2
	v_mov_b32_e32 v86, v2
	v_mov_b32_e32 v87, v2
	v_mov_b32_e32 v88, v2
	v_mov_b32_e32 v89, v2
	v_mov_b32_e32 v94, v2
	v_mov_b32_e32 v95, v2
	v_mov_b32_e32 v96, v2
	v_mov_b32_e32 v97, v2
	v_mov_b32_e32 v102, v2
	v_mov_b32_e32 v103, v2
	v_mov_b32_e32 v104, v2
	v_mov_b32_e32 v105, v2
	v_mov_b32_e32 v110, v2
	v_mov_b32_e32 v111, v2
	v_mov_b32_e32 v112, v2
	v_mov_b32_e32 v113, v2
	v_mov_b32_e32 v118, v2
	v_mov_b32_e32 v119, v2
	v_mov_b32_e32 v120, v2
	v_mov_b32_e32 v121, v2
	v_mov_b32_e32 v126, v2
	v_mov_b32_e32 v127, v2
	v_mov_b32_e32 v128, v2
	v_mov_b32_e32 v129, v2
